# attention second-half row sums as a packed-add tree in the post-barrier section (both main loops)
# baseline (speedup 1.0000x reference)
; DI float rowmax32(const f32x16& p0, const f32x16& p1) {
;     float a = fmaxf(fmaxf(p0[0], p0[1]), p1[0]), b = fmaxf(fmaxf(p0[2], p0[3]), p1[1]); a = fmaxf(fmaxf(a, p1[2]), p1[3]);
; #pragma unroll
;     for (int r = 4; r < 16; r += 4) { a = fmaxf(fmaxf(a, p0[r]), p0[r + 1]); b = fmaxf(fmaxf(b, p0[r + 2]), p0[r + 3]); a = fmaxf(fmaxf(a, p1[r]), p1[r + 1]); b = fmaxf(fmaxf(b, p1[r + 2]), p1[r + 3]); }
;     const float m = fmaxf(a, b);
;     const auto rr = __builtin_amdgcn_permlane32_swap(__float_as_uint(m), __float_as_uint(m), false, false);
;     return fmaxf(__uint_as_float(rr[0]), __uint_as_float(rr[1]));
.LBB0_817:
	s_or_b64 exec, exec, s[8:9]
	global_load_dwordx4 v[146:149], v160, s[56:57] offset:256
	v_add_u32_e32 v150, 0x6000, v150
	v_add_u32_e32 v152, 0x6000, v152
	v_add_u32_e32 v160, 0x100, v160
	v_pk_add_f32 v[50:51], v[50:51], v[66:67]
	v_max_f32_e32 v252, v82, v83
	v_pk_add_f32 v[52:53], v[52:53], v[68:69]
	v_max_f32_e32 v253, v84, v85
	v_pk_add_f32 v[54:55], v[54:55], v[70:71]
	v_max3_f32 v252, v252, v86, v87
	v_pk_add_f32 v[56:57], v[56:57], v[72:73]
	v_max3_f32 v253, v253, v88, v89
	v_pk_add_f32 v[58:59], v[58:59], v[74:75]
	v_max3_f32 v252, v252, v90, v91
	v_pk_add_f32 v[60:61], v[60:61], v[76:77]
	v_max3_f32 v253, v253, v92, v93
	v_pk_add_f32 v[62:63], v[62:63], v[78:79]
	v_max3_f32 v252, v252, v94, v95
	v_pk_add_f32 v[64:65], v[64:65], v[80:81]
	v_max3_f32 v253, v253, v96, v97
	v_pk_add_f32 v[50:51], v[50:51], v[58:59]
	v_max3_f32 v252, v252, v98, v99
	v_pk_add_f32 v[52:53], v[52:53], v[60:61]
	v_max3_f32 v253, v253, v100, v101
	v_pk_add_f32 v[54:55], v[54:55], v[62:63]
	v_max3_f32 v252, v252, v102, v103
	v_pk_add_f32 v[56:57], v[56:57], v[64:65]
	v_max3_f32 v253, v253, v104, v105
	v_pk_add_f32 v[50:51], v[50:51], v[54:55]
	v_max3_f32 v252, v252, v106, v107
	v_pk_add_f32 v[52:53], v[52:53], v[56:57]
	v_max3_f32 v253, v253, v108, v109
	v_pk_add_f32 v[50:51], v[50:51], v[52:53]
	v_max3_f32 v252, v252, v110, v111
	v_max3_f32 v253, v253, v112, v113
	v_add_f32_e32 v50, v50, v51
	v_max_f32_e32 v252, v252, v253
	v_mov_b32_e32 v253, v252
	v_add_f32_e32 v180, v203, v50
	s_nop 0
	v_permlane32_swap_b32_e32 v252, v253
	v_max_f32_e32 v51, v252, v253
	v_cmp_lt_f32_e32 vcc, s97, v51
	s_cbranch_vccnz .Lat1_resc_b
	v_mov_b32_e32 v205, v204

; DI float rowmax32(const f32x16& p0, const f32x16& p1) {
;     float a = fmaxf(fmaxf(p0[0], p0[1]), p1[0]), b = fmaxf(fmaxf(p0[2], p0[3]), p1[1]); a = fmaxf(fmaxf(a, p1[2]), p1[3]);
; #pragma unroll
;     for (int r = 4; r < 16; r += 4) { a = fmaxf(fmaxf(a, p0[r]), p0[r + 1]); b = fmaxf(fmaxf(b, p0[r + 2]), p0[r + 3]); a = fmaxf(fmaxf(a, p1[r]), p1[r + 1]); b = fmaxf(fmaxf(b, p1[r + 2]), p1[r + 3]); }
;     const float m = fmaxf(a, b);
;     const auto rr = __builtin_amdgcn_permlane32_swap(__float_as_uint(m), __float_as_uint(m), false, false);
;     return fmaxf(__uint_as_float(rr[0]), __uint_as_float(rr[1]));
.LBB0_873:
	s_or_b64 exec, exec, s[8:9]
	global_load_dwordx4 v[160:163], v182, s[56:57] offset:256
	v_add_u32_e32 v178, 0x6000, v178
	v_add_u32_e32 v180, 0x6000, v180
	v_add_u32_e32 v182, 0x100, v182
	v_pk_add_f32 v[64:65], v[64:65], v[80:81]
	v_max_f32_e32 v252, v96, v97
	v_pk_add_f32 v[66:67], v[66:67], v[82:83]
	v_max_f32_e32 v253, v98, v99
	v_pk_add_f32 v[68:69], v[68:69], v[84:85]
	v_max3_f32 v252, v252, v100, v101
	v_pk_add_f32 v[70:71], v[70:71], v[86:87]
	v_max3_f32 v253, v253, v102, v103
	v_pk_add_f32 v[72:73], v[72:73], v[88:89]
	v_max3_f32 v252, v252, v104, v105
	v_pk_add_f32 v[74:75], v[74:75], v[90:91]
	v_max3_f32 v253, v253, v106, v107
	v_pk_add_f32 v[76:77], v[76:77], v[92:93]
	v_max3_f32 v252, v252, v108, v109
	v_pk_add_f32 v[78:79], v[78:79], v[94:95]
	v_max3_f32 v253, v253, v110, v111
	v_pk_add_f32 v[64:65], v[64:65], v[72:73]
	v_max3_f32 v252, v252, v112, v113
	v_pk_add_f32 v[66:67], v[66:67], v[74:75]
	v_max3_f32 v253, v253, v114, v115
	v_pk_add_f32 v[68:69], v[68:69], v[76:77]
	v_max3_f32 v252, v252, v116, v117
	v_pk_add_f32 v[70:71], v[70:71], v[78:79]
	v_max3_f32 v253, v253, v118, v119
	v_pk_add_f32 v[64:65], v[64:65], v[68:69]
	v_max3_f32 v252, v252, v120, v121
	v_pk_add_f32 v[66:67], v[66:67], v[70:71]
	v_max3_f32 v253, v253, v122, v123
	v_pk_add_f32 v[64:65], v[64:65], v[66:67]
	v_max3_f32 v252, v252, v124, v125
	v_max3_f32 v253, v253, v126, v127
	v_add_f32_e32 v64, v64, v65
	v_max_f32_e32 v252, v252, v253
	v_mov_b32_e32 v253, v252
	v_add_f32_e32 v188, v208, v64
	s_nop 0
	v_permlane32_swap_b32_e32 v252, v253
	v_max_f32_e32 v3, v252, v253
	v_cmp_lt_f32_e32 vcc, s97, v3
	s_cbranch_vccnz .Lat2_resc_b
	v_mov_b32_e32 v210, v209
